# adaLN-table phase: silu(c) fill loop de-serialised too (32 loads up front, counted vmcnt, LDS offsets as immediates)
# speedup vs baseline: 1.0215x; 1.0091x over previous
; __device__ __forceinline__ void phase_prep(const Args& a, LAS unsigned char* lds) {
;     ...
;             if (!have) { const float* c = a.in[1];
;                 for (int e = tid; e < 16 * 1024; e += NTHREADS) { const int b = e >> 10, k = e & 1023; const float x = c[e]; sc[k * 16 + b] = x / (1.f + __expf(-x)); }
.LBB0_11:
	s_nor_b64 s[12:13], s[2:3], s[10:11]
	s_and_saveexec_b64 s[10:11], s[12:13]
	s_cbranch_execz .LBB0_14
	s_mov_b64 s[12:13], 0
	v_mov_b64_e32 v[2:3], v[30:31]
	v_mov_b32_e32 v4, v55
	v_mov_b32_e32 v5, v26
	s_mov_b32 s14, s70
	s_mov_b32 s15, s71
	v_lshlrev_b32_e32 v4, 2, v26
	v_lshlrev_b32_e32 v5, 2, v55
	global_load_dword v58, v4, s[14:15]
	s_add_u32 s14, s14, 0x800
	s_addc_u32 s15, s15, 0
	global_load_dword v59, v4, s[14:15]
	s_add_u32 s14, s14, 0x800
	s_addc_u32 s15, s15, 0
	global_load_dword v60, v4, s[14:15]
	s_add_u32 s14, s14, 0x800
	s_addc_u32 s15, s15, 0
	global_load_dword v61, v4, s[14:15]
	s_add_u32 s14, s14, 0x800
	s_addc_u32 s15, s15, 0
	global_load_dword v62, v4, s[14:15]
	s_add_u32 s14, s14, 0x800
	s_addc_u32 s15, s15, 0
	global_load_dword v63, v4, s[14:15]
	s_add_u32 s14, s14, 0x800
	s_addc_u32 s15, s15, 0
	global_load_dword v64, v4, s[14:15]
	s_add_u32 s14, s14, 0x800
	s_addc_u32 s15, s15, 0
	global_load_dword v65, v4, s[14:15]
	s_add_u32 s14, s14, 0x800
	s_addc_u32 s15, s15, 0
	global_load_dword v66, v4, s[14:15]
	s_add_u32 s14, s14, 0x800
	s_addc_u32 s15, s15, 0
	global_load_dword v67, v4, s[14:15]
	s_add_u32 s14, s14, 0x800
	s_addc_u32 s15, s15, 0
	global_load_dword v68, v4, s[14:15]
	s_add_u32 s14, s14, 0x800
	s_addc_u32 s15, s15, 0
	global_load_dword v69, v4, s[14:15]
	s_add_u32 s14, s14, 0x800
	s_addc_u32 s15, s15, 0
	global_load_dword v70, v4, s[14:15]
	s_add_u32 s14, s14, 0x800
	s_addc_u32 s15, s15, 0
	global_load_dword v71, v4, s[14:15]
	s_add_u32 s14, s14, 0x800
	s_addc_u32 s15, s15, 0
	global_load_dword v72, v4, s[14:15]
	s_add_u32 s14, s14, 0x800
	s_addc_u32 s15, s15, 0
	global_load_dword v73, v4, s[14:15]
	s_add_u32 s14, s14, 0x800
	s_addc_u32 s15, s15, 0
	global_load_dword v74, v4, s[14:15]
	s_add_u32 s14, s14, 0x800
	s_addc_u32 s15, s15, 0
	global_load_dword v75, v4, s[14:15]
	s_add_u32 s14, s14, 0x800
	s_addc_u32 s15, s15, 0
	global_load_dword v76, v4, s[14:15]
	s_add_u32 s14, s14, 0x800
	s_addc_u32 s15, s15, 0
	global_load_dword v77, v4, s[14:15]
	s_add_u32 s14, s14, 0x800
	s_addc_u32 s15, s15, 0
	global_load_dword v78, v4, s[14:15]
	s_add_u32 s14, s14, 0x800
	s_addc_u32 s15, s15, 0
	global_load_dword v79, v4, s[14:15]
	s_add_u32 s14, s14, 0x800
	s_addc_u32 s15, s15, 0
	global_load_dword v80, v4, s[14:15]
	s_add_u32 s14, s14, 0x800
	s_addc_u32 s15, s15, 0
	global_load_dword v81, v4, s[14:15]
	s_add_u32 s14, s14, 0x800
	s_addc_u32 s15, s15, 0
	global_load_dword v82, v4, s[14:15]
	s_add_u32 s14, s14, 0x800
	s_addc_u32 s15, s15, 0
	global_load_dword v83, v4, s[14:15]
	s_add_u32 s14, s14, 0x800
	s_addc_u32 s15, s15, 0
	global_load_dword v84, v4, s[14:15]
	s_add_u32 s14, s14, 0x800
	s_addc_u32 s15, s15, 0
	global_load_dword v85, v4, s[14:15]
	s_add_u32 s14, s14, 0x800
	s_addc_u32 s15, s15, 0
	global_load_dword v86, v4, s[14:15]
	s_add_u32 s14, s14, 0x800
	s_addc_u32 s15, s15, 0
	global_load_dword v87, v4, s[14:15]
	s_add_u32 s14, s14, 0x800
	s_addc_u32 s15, s15, 0
	global_load_dword v88, v4, s[14:15]
	s_add_u32 s14, s14, 0x800
	s_addc_u32 s15, s15, 0
	global_load_dword v89, v4, s[14:15]
	s_add_u32 s14, s14, 0x800
	s_addc_u32 s15, s15, 0
	s_waitcnt vmcnt(31)
	v_mul_f32_e32 v9, 0xbfb8aa3b, v58
	v_exp_f32_e32 v9, v9
	s_nop 0
	v_add_f32_e32 v8, 1.0, v9
	v_div_scale_f32 v9, s[14:15], v8, v8, v58
	v_rcp_f32_e32 v10, v9
	v_div_scale_f32 v11, vcc, v58, v8, v58
	v_fma_f32 v12, -v9, v10, 1.0
	v_fmac_f32_e32 v10, v12, v10
	v_mul_f32_e32 v12, v11, v10
	v_fma_f32 v13, -v9, v12, v11
	v_fmac_f32_e32 v12, v13, v10
	v_fma_f32 v9, -v9, v12, v11
	v_div_fmas_f32 v9, v9, v10, v12
	v_div_fixup_f32 v6, v9, v8, v58
	ds_write_b32 v5, v6
	s_waitcnt vmcnt(30)
	v_mul_f32_e32 v9, 0xbfb8aa3b, v59
	v_exp_f32_e32 v9, v9
	s_nop 0
	v_add_f32_e32 v8, 1.0, v9
	v_div_scale_f32 v9, s[14:15], v8, v8, v59
	v_rcp_f32_e32 v10, v9
	v_div_scale_f32 v11, vcc, v59, v8, v59
	v_fma_f32 v12, -v9, v10, 1.0
	v_fmac_f32_e32 v10, v12, v10
	v_mul_f32_e32 v12, v11, v10
	v_fma_f32 v13, -v9, v12, v11
	v_fmac_f32_e32 v12, v13, v10
	v_fma_f32 v9, -v9, v12, v11
	v_div_fmas_f32 v9, v9, v10, v12
	v_div_fixup_f32 v6, v9, v8, v59
	ds_write_b32 v5, v6 offset:32768
	s_waitcnt vmcnt(29)
	v_mul_f32_e32 v9, 0xbfb8aa3b, v60
	v_exp_f32_e32 v9, v9
	s_nop 0
	v_add_f32_e32 v8, 1.0, v9
	v_div_scale_f32 v9, s[14:15], v8, v8, v60
	v_rcp_f32_e32 v10, v9
	v_div_scale_f32 v11, vcc, v60, v8, v60
	v_fma_f32 v12, -v9, v10, 1.0
	v_fmac_f32_e32 v10, v12, v10
	v_mul_f32_e32 v12, v11, v10
	v_fma_f32 v13, -v9, v12, v11
	v_fmac_f32_e32 v12, v13, v10
	v_fma_f32 v9, -v9, v12, v11
	v_div_fmas_f32 v9, v9, v10, v12
	v_div_fixup_f32 v6, v9, v8, v60
	ds_write_b32 v5, v6 offset:4
	s_waitcnt vmcnt(28)
	v_mul_f32_e32 v9, 0xbfb8aa3b, v61
	v_exp_f32_e32 v9, v9
	s_nop 0
	v_add_f32_e32 v8, 1.0, v9
	v_div_scale_f32 v9, s[14:15], v8, v8, v61
	v_rcp_f32_e32 v10, v9
	v_div_scale_f32 v11, vcc, v61, v8, v61
	v_fma_f32 v12, -v9, v10, 1.0
	v_fmac_f32_e32 v10, v12, v10
	v_mul_f32_e32 v12, v11, v10
	v_fma_f32 v13, -v9, v12, v11
	v_fmac_f32_e32 v12, v13, v10
	v_fma_f32 v9, -v9, v12, v11
	v_div_fmas_f32 v9, v9, v10, v12
	v_div_fixup_f32 v6, v9, v8, v61
	ds_write_b32 v5, v6 offset:32772
	s_waitcnt vmcnt(27)
	v_mul_f32_e32 v9, 0xbfb8aa3b, v62
	v_exp_f32_e32 v9, v9
	s_nop 0
	v_add_f32_e32 v8, 1.0, v9
	v_div_scale_f32 v9, s[14:15], v8, v8, v62
	v_rcp_f32_e32 v10, v9
	v_div_scale_f32 v11, vcc, v62, v8, v62
	v_fma_f32 v12, -v9, v10, 1.0
	v_fmac_f32_e32 v10, v12, v10
	v_mul_f32_e32 v12, v11, v10
	v_fma_f32 v13, -v9, v12, v11
	v_fmac_f32_e32 v12, v13, v10
	v_fma_f32 v9, -v9, v12, v11
	v_div_fmas_f32 v9, v9, v10, v12
	v_div_fixup_f32 v6, v9, v8, v62
	ds_write_b32 v5, v6 offset:8
	s_waitcnt vmcnt(26)
; __device__ __forceinline__ void phase_prep(const Args& a, LAS unsigned char* lds) {
;     ...
;                 for (int e = tid; e < 16 * 1024; e += NTHREADS) { const int b = e >> 10, k = e & 1023; const float x = c[e]; sc[k * 16 + b] = x / (1.f + __expf(-x)); }
	v_mul_f32_e32 v9, 0xbfb8aa3b, v63
	v_exp_f32_e32 v9, v9
	s_nop 0
	v_add_f32_e32 v8, 1.0, v9
	v_div_scale_f32 v9, s[14:15], v8, v8, v63
	v_rcp_f32_e32 v10, v9
	v_div_scale_f32 v11, vcc, v63, v8, v63
	v_fma_f32 v12, -v9, v10, 1.0
	v_fmac_f32_e32 v10, v12, v10
	v_mul_f32_e32 v12, v11, v10
	v_fma_f32 v13, -v9, v12, v11
	v_fmac_f32_e32 v12, v13, v10
	v_fma_f32 v9, -v9, v12, v11
	v_div_fmas_f32 v9, v9, v10, v12
	v_div_fixup_f32 v6, v9, v8, v63
	ds_write_b32 v5, v6 offset:32776
	s_waitcnt vmcnt(25)
	v_mul_f32_e32 v9, 0xbfb8aa3b, v64
	v_exp_f32_e32 v9, v9
	s_nop 0
	v_add_f32_e32 v8, 1.0, v9
	v_div_scale_f32 v9, s[14:15], v8, v8, v64
	v_rcp_f32_e32 v10, v9
	v_div_scale_f32 v11, vcc, v64, v8, v64
	v_fma_f32 v12, -v9, v10, 1.0
	v_fmac_f32_e32 v10, v12, v10
	v_mul_f32_e32 v12, v11, v10
	v_fma_f32 v13, -v9, v12, v11
	v_fmac_f32_e32 v12, v13, v10
	v_fma_f32 v9, -v9, v12, v11
	v_div_fmas_f32 v9, v9, v10, v12
	v_div_fixup_f32 v6, v9, v8, v64
	ds_write_b32 v5, v6 offset:12
	s_waitcnt vmcnt(24)
	v_mul_f32_e32 v9, 0xbfb8aa3b, v65
	v_exp_f32_e32 v9, v9
	s_nop 0
	v_add_f32_e32 v8, 1.0, v9
	v_div_scale_f32 v9, s[14:15], v8, v8, v65
	v_rcp_f32_e32 v10, v9
	v_div_scale_f32 v11, vcc, v65, v8, v65
	v_fma_f32 v12, -v9, v10, 1.0
	v_fmac_f32_e32 v10, v12, v10
	v_mul_f32_e32 v12, v11, v10
	v_fma_f32 v13, -v9, v12, v11
	v_fmac_f32_e32 v12, v13, v10
	v_fma_f32 v9, -v9, v12, v11
	v_div_fmas_f32 v9, v9, v10, v12
	v_div_fixup_f32 v6, v9, v8, v65
	ds_write_b32 v5, v6 offset:32780
	s_waitcnt vmcnt(23)
	v_mul_f32_e32 v9, 0xbfb8aa3b, v66
	v_exp_f32_e32 v9, v9
	s_nop 0
	v_add_f32_e32 v8, 1.0, v9
	v_div_scale_f32 v9, s[14:15], v8, v8, v66
	v_rcp_f32_e32 v10, v9
	v_div_scale_f32 v11, vcc, v66, v8, v66
	v_fma_f32 v12, -v9, v10, 1.0
	v_fmac_f32_e32 v10, v12, v10
	v_mul_f32_e32 v12, v11, v10
	v_fma_f32 v13, -v9, v12, v11
	v_fmac_f32_e32 v12, v13, v10
	v_fma_f32 v9, -v9, v12, v11
	v_div_fmas_f32 v9, v9, v10, v12
	v_div_fixup_f32 v6, v9, v8, v66
	ds_write_b32 v5, v6 offset:16
	s_waitcnt vmcnt(22)
	v_mul_f32_e32 v9, 0xbfb8aa3b, v67
	v_exp_f32_e32 v9, v9
	s_nop 0
	v_add_f32_e32 v8, 1.0, v9
	v_div_scale_f32 v9, s[14:15], v8, v8, v67
	v_rcp_f32_e32 v10, v9
	v_div_scale_f32 v11, vcc, v67, v8, v67
	v_fma_f32 v12, -v9, v10, 1.0
	v_fmac_f32_e32 v10, v12, v10
	v_mul_f32_e32 v12, v11, v10
	v_fma_f32 v13, -v9, v12, v11
	v_fmac_f32_e32 v12, v13, v10
	v_fma_f32 v9, -v9, v12, v11
	v_div_fmas_f32 v9, v9, v10, v12
	v_div_fixup_f32 v6, v9, v8, v67
	ds_write_b32 v5, v6 offset:32784
	s_waitcnt vmcnt(21)
	v_mul_f32_e32 v9, 0xbfb8aa3b, v68
	v_exp_f32_e32 v9, v9
	s_nop 0
	v_add_f32_e32 v8, 1.0, v9
	v_div_scale_f32 v9, s[14:15], v8, v8, v68
	v_rcp_f32_e32 v10, v9
	v_div_scale_f32 v11, vcc, v68, v8, v68
	v_fma_f32 v12, -v9, v10, 1.0
	v_fmac_f32_e32 v10, v12, v10
	v_mul_f32_e32 v12, v11, v10
	v_fma_f32 v13, -v9, v12, v11
	v_fmac_f32_e32 v12, v13, v10
	v_fma_f32 v9, -v9, v12, v11
	v_div_fmas_f32 v9, v9, v10, v12
	v_div_fixup_f32 v6, v9, v8, v68
	ds_write_b32 v5, v6 offset:20
	s_waitcnt vmcnt(20)
	v_mul_f32_e32 v9, 0xbfb8aa3b, v69
	v_exp_f32_e32 v9, v9
	s_nop 0
	v_add_f32_e32 v8, 1.0, v9
	v_div_scale_f32 v9, s[14:15], v8, v8, v69
	v_rcp_f32_e32 v10, v9
	v_div_scale_f32 v11, vcc, v69, v8, v69
	v_fma_f32 v12, -v9, v10, 1.0
	v_fmac_f32_e32 v10, v12, v10
	v_mul_f32_e32 v12, v11, v10
	v_fma_f32 v13, -v9, v12, v11
	v_fmac_f32_e32 v12, v13, v10
	v_fma_f32 v9, -v9, v12, v11
	v_div_fmas_f32 v9, v9, v10, v12
	v_div_fixup_f32 v6, v9, v8, v69
	ds_write_b32 v5, v6 offset:32788
	s_waitcnt vmcnt(19)
	v_mul_f32_e32 v9, 0xbfb8aa3b, v70
	v_exp_f32_e32 v9, v9
	s_nop 0
	v_add_f32_e32 v8, 1.0, v9
	v_div_scale_f32 v9, s[14:15], v8, v8, v70
	v_rcp_f32_e32 v10, v9
	v_div_scale_f32 v11, vcc, v70, v8, v70
	v_fma_f32 v12, -v9, v10, 1.0
	v_fmac_f32_e32 v10, v12, v10
	v_mul_f32_e32 v12, v11, v10
	v_fma_f32 v13, -v9, v12, v11
	v_fmac_f32_e32 v12, v13, v10
	v_fma_f32 v9, -v9, v12, v11
	v_div_fmas_f32 v9, v9, v10, v12
	v_div_fixup_f32 v6, v9, v8, v70
	ds_write_b32 v5, v6 offset:24
	s_waitcnt vmcnt(18)
	v_mul_f32_e32 v9, 0xbfb8aa3b, v71
	v_exp_f32_e32 v9, v9
	s_nop 0
	v_add_f32_e32 v8, 1.0, v9
	v_div_scale_f32 v9, s[14:15], v8, v8, v71
	v_rcp_f32_e32 v10, v9
	v_div_scale_f32 v11, vcc, v71, v8, v71
	v_fma_f32 v12, -v9, v10, 1.0
	v_fmac_f32_e32 v10, v12, v10
	v_mul_f32_e32 v12, v11, v10
	v_fma_f32 v13, -v9, v12, v11
	v_fmac_f32_e32 v12, v13, v10
	v_fma_f32 v9, -v9, v12, v11
	v_div_fmas_f32 v9, v9, v10, v12
	v_div_fixup_f32 v6, v9, v8, v71
	ds_write_b32 v5, v6 offset:32792
	s_waitcnt vmcnt(17)
	v_mul_f32_e32 v9, 0xbfb8aa3b, v72
	v_exp_f32_e32 v9, v9
	s_nop 0
	v_add_f32_e32 v8, 1.0, v9
	v_div_scale_f32 v9, s[14:15], v8, v8, v72
	v_rcp_f32_e32 v10, v9
	v_div_scale_f32 v11, vcc, v72, v8, v72
	v_fma_f32 v12, -v9, v10, 1.0
	v_fmac_f32_e32 v10, v12, v10
	v_mul_f32_e32 v12, v11, v10
	v_fma_f32 v13, -v9, v12, v11
	v_fmac_f32_e32 v12, v13, v10
	v_fma_f32 v9, -v9, v12, v11
	v_div_fmas_f32 v9, v9, v10, v12
	v_div_fixup_f32 v6, v9, v8, v72
	ds_write_b32 v5, v6 offset:28
	s_waitcnt vmcnt(16)
	v_mul_f32_e32 v9, 0xbfb8aa3b, v73
	v_exp_f32_e32 v9, v9
	s_nop 0
	v_add_f32_e32 v8, 1.0, v9
	v_div_scale_f32 v9, s[14:15], v8, v8, v73
	v_rcp_f32_e32 v10, v9
	v_div_scale_f32 v11, vcc, v73, v8, v73
	v_fma_f32 v12, -v9, v10, 1.0
	v_fmac_f32_e32 v10, v12, v10
	v_mul_f32_e32 v12, v11, v10
	v_fma_f32 v13, -v9, v12, v11
	v_fmac_f32_e32 v12, v13, v10
	v_fma_f32 v9, -v9, v12, v11
	v_div_fmas_f32 v9, v9, v10, v12
	v_div_fixup_f32 v6, v9, v8, v73
	ds_write_b32 v5, v6 offset:32796
	s_waitcnt vmcnt(15)
; __device__ __forceinline__ void phase_prep(const Args& a, LAS unsigned char* lds) {
;     ...
;                 for (int e = tid; e < 16 * 1024; e += NTHREADS) { const int b = e >> 10, k = e & 1023; const float x = c[e]; sc[k * 16 + b] = x / (1.f + __expf(-x)); }
	v_mul_f32_e32 v9, 0xbfb8aa3b, v74
	v_exp_f32_e32 v9, v9
	s_nop 0
	v_add_f32_e32 v8, 1.0, v9
	v_div_scale_f32 v9, s[14:15], v8, v8, v74
	v_rcp_f32_e32 v10, v9
	v_div_scale_f32 v11, vcc, v74, v8, v74
	v_fma_f32 v12, -v9, v10, 1.0
	v_fmac_f32_e32 v10, v12, v10
	v_mul_f32_e32 v12, v11, v10
	v_fma_f32 v13, -v9, v12, v11
	v_fmac_f32_e32 v12, v13, v10
	v_fma_f32 v9, -v9, v12, v11
	v_div_fmas_f32 v9, v9, v10, v12
	v_div_fixup_f32 v6, v9, v8, v74
	ds_write_b32 v5, v6 offset:32
	s_waitcnt vmcnt(14)
	v_mul_f32_e32 v9, 0xbfb8aa3b, v75
	v_exp_f32_e32 v9, v9
	s_nop 0
	v_add_f32_e32 v8, 1.0, v9
	v_div_scale_f32 v9, s[14:15], v8, v8, v75
	v_rcp_f32_e32 v10, v9
	v_div_scale_f32 v11, vcc, v75, v8, v75
	v_fma_f32 v12, -v9, v10, 1.0
	v_fmac_f32_e32 v10, v12, v10
	v_mul_f32_e32 v12, v11, v10
	v_fma_f32 v13, -v9, v12, v11
	v_fmac_f32_e32 v12, v13, v10
	v_fma_f32 v9, -v9, v12, v11
	v_div_fmas_f32 v9, v9, v10, v12
	v_div_fixup_f32 v6, v9, v8, v75
	ds_write_b32 v5, v6 offset:32800
	s_waitcnt vmcnt(13)
	v_mul_f32_e32 v9, 0xbfb8aa3b, v76
	v_exp_f32_e32 v9, v9
	s_nop 0
	v_add_f32_e32 v8, 1.0, v9
	v_div_scale_f32 v9, s[14:15], v8, v8, v76
	v_rcp_f32_e32 v10, v9
	v_div_scale_f32 v11, vcc, v76, v8, v76
	v_fma_f32 v12, -v9, v10, 1.0
	v_fmac_f32_e32 v10, v12, v10
	v_mul_f32_e32 v12, v11, v10
	v_fma_f32 v13, -v9, v12, v11
	v_fmac_f32_e32 v12, v13, v10
	v_fma_f32 v9, -v9, v12, v11
	v_div_fmas_f32 v9, v9, v10, v12
	v_div_fixup_f32 v6, v9, v8, v76
	ds_write_b32 v5, v6 offset:36
	s_waitcnt vmcnt(12)
	v_mul_f32_e32 v9, 0xbfb8aa3b, v77
	v_exp_f32_e32 v9, v9
	s_nop 0
	v_add_f32_e32 v8, 1.0, v9
	v_div_scale_f32 v9, s[14:15], v8, v8, v77
	v_rcp_f32_e32 v10, v9
	v_div_scale_f32 v11, vcc, v77, v8, v77
	v_fma_f32 v12, -v9, v10, 1.0
	v_fmac_f32_e32 v10, v12, v10
	v_mul_f32_e32 v12, v11, v10
	v_fma_f32 v13, -v9, v12, v11
	v_fmac_f32_e32 v12, v13, v10
	v_fma_f32 v9, -v9, v12, v11
	v_div_fmas_f32 v9, v9, v10, v12
	v_div_fixup_f32 v6, v9, v8, v77
	ds_write_b32 v5, v6 offset:32804
	s_waitcnt vmcnt(11)
	v_mul_f32_e32 v9, 0xbfb8aa3b, v78
	v_exp_f32_e32 v9, v9
	s_nop 0
	v_add_f32_e32 v8, 1.0, v9
	v_div_scale_f32 v9, s[14:15], v8, v8, v78
	v_rcp_f32_e32 v10, v9
	v_div_scale_f32 v11, vcc, v78, v8, v78
	v_fma_f32 v12, -v9, v10, 1.0
	v_fmac_f32_e32 v10, v12, v10
	v_mul_f32_e32 v12, v11, v10
	v_fma_f32 v13, -v9, v12, v11
	v_fmac_f32_e32 v12, v13, v10
	v_fma_f32 v9, -v9, v12, v11
	v_div_fmas_f32 v9, v9, v10, v12
	v_div_fixup_f32 v6, v9, v8, v78
	ds_write_b32 v5, v6 offset:40
	s_waitcnt vmcnt(10)
	v_mul_f32_e32 v9, 0xbfb8aa3b, v79
	v_exp_f32_e32 v9, v9
	s_nop 0
	v_add_f32_e32 v8, 1.0, v9
	v_div_scale_f32 v9, s[14:15], v8, v8, v79
	v_rcp_f32_e32 v10, v9
	v_div_scale_f32 v11, vcc, v79, v8, v79
	v_fma_f32 v12, -v9, v10, 1.0
	v_fmac_f32_e32 v10, v12, v10
	v_mul_f32_e32 v12, v11, v10
	v_fma_f32 v13, -v9, v12, v11
	v_fmac_f32_e32 v12, v13, v10
	v_fma_f32 v9, -v9, v12, v11
	v_div_fmas_f32 v9, v9, v10, v12
	v_div_fixup_f32 v6, v9, v8, v79
	ds_write_b32 v5, v6 offset:32808
	s_waitcnt vmcnt(9)
	v_mul_f32_e32 v9, 0xbfb8aa3b, v80
	v_exp_f32_e32 v9, v9
	s_nop 0
	v_add_f32_e32 v8, 1.0, v9
	v_div_scale_f32 v9, s[14:15], v8, v8, v80
	v_rcp_f32_e32 v10, v9
	v_div_scale_f32 v11, vcc, v80, v8, v80
	v_fma_f32 v12, -v9, v10, 1.0
	v_fmac_f32_e32 v10, v12, v10
	v_mul_f32_e32 v12, v11, v10
	v_fma_f32 v13, -v9, v12, v11
	v_fmac_f32_e32 v12, v13, v10
	v_fma_f32 v9, -v9, v12, v11
	v_div_fmas_f32 v9, v9, v10, v12
	v_div_fixup_f32 v6, v9, v8, v80
	ds_write_b32 v5, v6 offset:44
	s_waitcnt vmcnt(8)
	v_mul_f32_e32 v9, 0xbfb8aa3b, v81
	v_exp_f32_e32 v9, v9
	s_nop 0
	v_add_f32_e32 v8, 1.0, v9
	v_div_scale_f32 v9, s[14:15], v8, v8, v81
	v_rcp_f32_e32 v10, v9
	v_div_scale_f32 v11, vcc, v81, v8, v81
	v_fma_f32 v12, -v9, v10, 1.0
	v_fmac_f32_e32 v10, v12, v10
	v_mul_f32_e32 v12, v11, v10
	v_fma_f32 v13, -v9, v12, v11
	v_fmac_f32_e32 v12, v13, v10
	v_fma_f32 v9, -v9, v12, v11
	v_div_fmas_f32 v9, v9, v10, v12
	v_div_fixup_f32 v6, v9, v8, v81
	ds_write_b32 v5, v6 offset:32812
	s_waitcnt vmcnt(7)
; __device__ __forceinline__ void phase_prep(const Args& a, LAS unsigned char* lds) {
;     ...
;                 for (int e = tid; e < 16 * 1024; e += NTHREADS) { const int b = e >> 10, k = e & 1023; const float x = c[e]; sc[k * 16 + b] = x / (1.f + __expf(-x)); }
	v_mul_f32_e32 v9, 0xbfb8aa3b, v82
	v_exp_f32_e32 v9, v9
	s_nop 0
	v_add_f32_e32 v8, 1.0, v9
	v_div_scale_f32 v9, s[14:15], v8, v8, v82
	v_rcp_f32_e32 v10, v9
	v_div_scale_f32 v11, vcc, v82, v8, v82
	v_fma_f32 v12, -v9, v10, 1.0
	v_fmac_f32_e32 v10, v12, v10
	v_mul_f32_e32 v12, v11, v10
	v_fma_f32 v13, -v9, v12, v11
	v_fmac_f32_e32 v12, v13, v10
	v_fma_f32 v9, -v9, v12, v11
	v_div_fmas_f32 v9, v9, v10, v12
	v_div_fixup_f32 v6, v9, v8, v82
	ds_write_b32 v5, v6 offset:48
	s_waitcnt vmcnt(6)
	v_mul_f32_e32 v9, 0xbfb8aa3b, v83
	v_exp_f32_e32 v9, v9
	s_nop 0
	v_add_f32_e32 v8, 1.0, v9
	v_div_scale_f32 v9, s[14:15], v8, v8, v83
	v_rcp_f32_e32 v10, v9
	v_div_scale_f32 v11, vcc, v83, v8, v83
	v_fma_f32 v12, -v9, v10, 1.0
	v_fmac_f32_e32 v10, v12, v10
	v_mul_f32_e32 v12, v11, v10
	v_fma_f32 v13, -v9, v12, v11
	v_fmac_f32_e32 v12, v13, v10
	v_fma_f32 v9, -v9, v12, v11
	v_div_fmas_f32 v9, v9, v10, v12
	v_div_fixup_f32 v6, v9, v8, v83
	ds_write_b32 v5, v6 offset:32816
	s_waitcnt vmcnt(5)
	v_mul_f32_e32 v9, 0xbfb8aa3b, v84
	v_exp_f32_e32 v9, v9
	s_nop 0
	v_add_f32_e32 v8, 1.0, v9
	v_div_scale_f32 v9, s[14:15], v8, v8, v84
	v_rcp_f32_e32 v10, v9
	v_div_scale_f32 v11, vcc, v84, v8, v84
	v_fma_f32 v12, -v9, v10, 1.0
	v_fmac_f32_e32 v10, v12, v10
	v_mul_f32_e32 v12, v11, v10
	v_fma_f32 v13, -v9, v12, v11
	v_fmac_f32_e32 v12, v13, v10
	v_fma_f32 v9, -v9, v12, v11
	v_div_fmas_f32 v9, v9, v10, v12
	v_div_fixup_f32 v6, v9, v8, v84
	ds_write_b32 v5, v6 offset:52
	s_waitcnt vmcnt(4)
	v_mul_f32_e32 v9, 0xbfb8aa3b, v85
	v_exp_f32_e32 v9, v9
	s_nop 0
	v_add_f32_e32 v8, 1.0, v9
	v_div_scale_f32 v9, s[14:15], v8, v8, v85
	v_rcp_f32_e32 v10, v9
	v_div_scale_f32 v11, vcc, v85, v8, v85
	v_fma_f32 v12, -v9, v10, 1.0
	v_fmac_f32_e32 v10, v12, v10
	v_mul_f32_e32 v12, v11, v10
	v_fma_f32 v13, -v9, v12, v11
	v_fmac_f32_e32 v12, v13, v10
	v_fma_f32 v9, -v9, v12, v11
	v_div_fmas_f32 v9, v9, v10, v12
	v_div_fixup_f32 v6, v9, v8, v85
	ds_write_b32 v5, v6 offset:32820
	s_waitcnt vmcnt(3)
	v_mul_f32_e32 v9, 0xbfb8aa3b, v86
	v_exp_f32_e32 v9, v9
	s_nop 0
	v_add_f32_e32 v8, 1.0, v9
	v_div_scale_f32 v9, s[14:15], v8, v8, v86
	v_rcp_f32_e32 v10, v9
	v_div_scale_f32 v11, vcc, v86, v8, v86
	v_fma_f32 v12, -v9, v10, 1.0
	v_fmac_f32_e32 v10, v12, v10
	v_mul_f32_e32 v12, v11, v10
	v_fma_f32 v13, -v9, v12, v11
	v_fmac_f32_e32 v12, v13, v10
	v_fma_f32 v9, -v9, v12, v11
	v_div_fmas_f32 v9, v9, v10, v12
	v_div_fixup_f32 v6, v9, v8, v86
	ds_write_b32 v5, v6 offset:56
	s_waitcnt vmcnt(2)
	v_mul_f32_e32 v9, 0xbfb8aa3b, v87
	v_exp_f32_e32 v9, v9
	s_nop 0
	v_add_f32_e32 v8, 1.0, v9
	v_div_scale_f32 v9, s[14:15], v8, v8, v87
	v_rcp_f32_e32 v10, v9
	v_div_scale_f32 v11, vcc, v87, v8, v87
	v_fma_f32 v12, -v9, v10, 1.0
	v_fmac_f32_e32 v10, v12, v10
	v_mul_f32_e32 v12, v11, v10
	v_fma_f32 v13, -v9, v12, v11
	v_fmac_f32_e32 v12, v13, v10
	v_fma_f32 v9, -v9, v12, v11
	v_div_fmas_f32 v9, v9, v10, v12
	v_div_fixup_f32 v6, v9, v8, v87
	ds_write_b32 v5, v6 offset:32824
	s_waitcnt vmcnt(1)
	v_mul_f32_e32 v9, 0xbfb8aa3b, v88
	v_exp_f32_e32 v9, v9
	s_nop 0
	v_add_f32_e32 v8, 1.0, v9
	v_div_scale_f32 v9, s[14:15], v8, v8, v88
	v_rcp_f32_e32 v10, v9
	v_div_scale_f32 v11, vcc, v88, v8, v88
	v_fma_f32 v12, -v9, v10, 1.0
	v_fmac_f32_e32 v10, v12, v10
	v_mul_f32_e32 v12, v11, v10
	v_fma_f32 v13, -v9, v12, v11
	v_fmac_f32_e32 v12, v13, v10
	v_fma_f32 v9, -v9, v12, v11
	v_div_fmas_f32 v9, v9, v10, v12
	v_div_fixup_f32 v6, v9, v8, v88
	ds_write_b32 v5, v6 offset:60
	s_waitcnt vmcnt(0)
	v_mul_f32_e32 v9, 0xbfb8aa3b, v89
	v_exp_f32_e32 v9, v9
	s_nop 0
	v_add_f32_e32 v8, 1.0, v9
	v_div_scale_f32 v9, s[14:15], v8, v8, v89
	v_rcp_f32_e32 v10, v9
	v_div_scale_f32 v11, vcc, v89, v8, v89
	v_fma_f32 v12, -v9, v10, 1.0
	v_fmac_f32_e32 v10, v12, v10
	v_mul_f32_e32 v12, v11, v10
	v_fma_f32 v13, -v9, v12, v11
	v_fmac_f32_e32 v12, v13, v10
	v_fma_f32 v9, -v9, v12, v11
	v_div_fmas_f32 v9, v9, v10, v12
	v_div_fixup_f32 v6, v9, v8, v89
	ds_write_b32 v5, v6 offset:32828
